# MLA K/V tiles fetched one step earlier into a second staging register set, rolling K/V fragment registers, counted vmcnt per wave type
# speedup vs baseline: 1.0321x; 1.0030x over previous
; #define QK0(j) ATTN_QK_STEP(sc_cur, Kc, j)
; template <bool MLA, int DK, int DV>
; __device__ __forceinline__ void attn_core(const Params& p, int b, int h, int map, int q0, int nt, char* smem,
;                                           f32x16 (&o)[DV / 32], float& lout) {
;     ...
;   ATTN_GLOADK(0);
;   ATTN_GLOADV(0);
;   ATTN_STOREK(0);
;   ATTN_STOREV(0);
;   if (nt > 1) { ATTN_GLOADK(1); ATTN_STOREK(1); }
;   __syncthreads();
;   f32x16 sc_cur[2], sc_nxt[2];
; #pragma unroll
;   for (int sub = 0; sub < 2; ++sub)
; #pragma unroll
;     for (int i = 0; i < 16; ++i) { sc_cur[sub][i] = 0.f; sc_nxt[sub][i] = 0.f; }
;   {
;     const bft* Kc = Ks;
;     ...
;     QK0(0) QK0(1) QK0(2) QK0(3) QK0(4) QK0(5)
;     if constexpr (NKS == 6) { QK0(6) QK0(7) QK0(8) QK0(9) QK0(10) QK0(11) }
;     ...
;     float mx = -INFINITY;
; #pragma unroll
;     for (int sub = 0; sub < 2; ++sub)
; #pragma unroll
;       for (int i = 0; i < 16; ++i) mx = fmaxf(mx, sc_cur[sub][i]);
;     mx = fmaxf(mx, __shfl_xor(mx, 32));
;     mrun = mx * sc;
.LBB0_541:
	s_or_b64 exec, exec, s[12:13]
	v_mul_u32_u24_e32 v7, 0x68, v10
	v_lshlrev_b32_e32 v14, 1, v14
	v_lshl_add_u32 v155, v7, 1, v14
	s_waitcnt lgkmcnt(0)
	s_barrier
	ds_read_b128 v[14:17], v155
	s_waitcnt vmcnt(56)
	ds_read_b128 v[32:35], v155 offset:32
	s_waitcnt vmcnt(5) lgkmcnt(1)
	v_mfma_f32_32x32x16_bf16 v[16:31], v[14:17], v[96:99], 0
	v_and_b32_e32 v15, 64, v197
	v_xor_b32_e32 v14, 32, v197
	v_add_u32_e32 v15, 64, v15
	v_cmp_lt_i32_e32 vcc, v14, v15
	v_add_u32_e32 v158, v12, v11
	v_readlane_b32 s60, v254, 40
	v_cndmask_b32_e32 v14, v197, v14, vcc
	s_waitcnt vmcnt(4) lgkmcnt(0)
	v_mfma_f32_32x32x16_bf16 v[16:31], v[32:35], v[100:103], v[16:31]
	ds_read_b128 v[32:35], v155 offset:64
	ds_read_b128 v[36:39], v155 offset:96
	v_lshlrev_b32_e32 v156, 2, v14
	v_readlane_b32 s61, v254, 41
	v_lshl_add_u64 v[146:147], v[4:5], 1, s[16:17]
	s_mov_b32 s78, s65
	v_lshl_add_u64 v[144:145], v[2:3], 1, s[60:61]
	s_mov_b32 s79, s65
	s_waitcnt vmcnt(3) lgkmcnt(1)
	v_mfma_f32_32x32x16_bf16 v[16:31], v[32:35], v[104:107], v[16:31]
	s_mov_b32 s64, s65
	s_mov_b32 s66, s65
	s_mov_b32 s67, s65
	s_mov_b32 s68, s65
	s_mov_b32 s69, s65
	s_mov_b32 s70, s65
	s_mov_b32 s71, s65
	s_waitcnt vmcnt(2) lgkmcnt(0)
	v_mfma_f32_32x32x16_bf16 v[16:31], v[36:39], v[108:111], v[16:31]
	ds_read_b128 v[32:35], v155 offset:128
	ds_read_b128 v[36:39], v155 offset:160
	s_mov_b32 s72, s65
	s_mov_b32 s73, s65
	s_mov_b32 s74, s65
	s_mov_b32 s75, s65
	s_mov_b32 s76, s65
	s_mov_b32 s77, s65
	s_waitcnt vmcnt(1) lgkmcnt(1)
	v_mfma_f32_32x32x16_bf16 v[16:31], v[32:35], v[112:115], v[16:31]
	v_mov_b64_e32 v[94:95], s[78:79]
	v_mov_b64_e32 v[80:81], s[64:65]
	v_mov_b64_e32 v[92:93], s[76:77]
	v_mov_b64_e32 v[90:91], s[74:75]
	v_mov_b64_e32 v[88:89], s[72:73]
	v_mov_b64_e32 v[86:87], s[70:71]
	v_mov_b64_e32 v[84:85], s[68:69]
	s_waitcnt vmcnt(0) lgkmcnt(0)
	v_mfma_f32_32x32x16_bf16 v[16:31], v[36:39], v[116:119], v[16:31]
	ds_read_b128 v[32:35], v155 offset:6656
	ds_read_b128 v[36:39], v155 offset:6688
	v_mov_b64_e32 v[82:83], s[66:67]
	v_lshlrev_b32_e32 v4, 1, v4
	v_mov_b64_e32 v[48:49], v[80:81]
	s_mov_b32 s53, s65
	s_mov_b32 s68, 3
	v_cmp_lt_i32_e64 s[14:15], 7, v6
	s_waitcnt lgkmcnt(1)
	v_mfma_f32_32x32x16_bf16 v[64:79], v[32:35], v[96:99], 0
	ds_read_b128 v[32:35], v155 offset:6720
	s_nop 0
	v_max3_f32 v7, v16, s55, v17
	v_max3_f32 v7, v7, v18, v19
	v_max3_f32 v7, v7, v20, v21
	v_max3_f32 v7, v7, v22, v23
	v_max3_f32 v7, v7, v24, v25
	v_max3_f32 v7, v7, v26, v27
	s_waitcnt lgkmcnt(1)
	v_mfma_f32_32x32x16_bf16 v[64:79], v[36:39], v[100:103], v[64:79]
	ds_read_b128 v[36:39], v155 offset:6752
	v_max3_f32 v7, v7, v28, v29
	v_max3_f32 v7, v7, v30, v31
	v_mov_b64_e32 v[50:51], v[82:83]
	v_mov_b64_e32 v[52:53], v[84:85]
	v_mov_b64_e32 v[54:55], v[86:87]
	v_mov_b64_e32 v[56:57], v[88:89]
	s_waitcnt lgkmcnt(1)
	v_mfma_f32_32x32x16_bf16 v[64:79], v[32:35], v[104:107], v[64:79]
	ds_read_b128 v[32:35], v155 offset:6784
	v_mov_b64_e32 v[58:59], v[90:91]
	v_mov_b64_e32 v[60:61], v[92:93]
	v_mov_b64_e32 v[62:63], v[94:95]
	s_waitcnt lgkmcnt(1)
	v_mfma_f32_32x32x16_bf16 v[64:79], v[36:39], v[108:111], v[64:79]
	ds_read_b128 v[36:39], v155 offset:6816
	s_waitcnt lgkmcnt(0)
	s_barrier
; template <bool MLA, int DK, int DV>
; __device__ __forceinline__ void attn_core(const Params& p, int b, int h, int map, int q0, int nt, char* smem,
;                                           f32x16 (&o)[DV / 32], float& lout) {
;     ...
;     float mx = -INFINITY;
; #pragma unroll
;     for (int sub = 0; sub < 2; ++sub)
; #pragma unroll
;       for (int i = 0; i < 16; ++i) mx = fmaxf(mx, sc_cur[sub][i]);
;     mx = fmaxf(mx, __shfl_xor(mx, 32));
;     mrun = mx * sc;
;   }
	v_mfma_f32_32x32x16_bf16 v[64:79], v[32:35], v[112:115], v[64:79]
	v_mov_b32_e32 v32, 0
	v_mfma_f32_32x32x16_bf16 v[64:79], v[36:39], v[116:119], v[64:79]
	s_nop 11
	v_max3_f32 v7, v7, v64, v65
	v_max3_f32 v7, v7, v66, v67
	v_max3_f32 v7, v7, v68, v69
	v_max3_f32 v7, v7, v70, v71
	v_max3_f32 v7, v7, v72, v73
	v_max3_f32 v7, v7, v74, v75
	v_max3_f32 v7, v7, v76, v77
	v_max3_f32 v7, v7, v78, v79
	ds_bpermute_b32 v14, v156, v7
	s_waitcnt lgkmcnt(0)
	v_max_f32_e32 v14, v14, v14
	v_max_f32_e32 v7, v7, v14
	v_mul_f32_e32 v162, 1.0, v7
	v_mul_u32_u24_e32 v7, 0x44, v10
	v_lshlrev_b32_e32 v7, 1, v7
	v_lshl_add_u32 v157, v9, 3, v7
	v_mul_lo_u32 v7, v158, 12
	v_sub_u32_e32 v7, v8, v7
	v_lshlrev_b32_e32 v160, 3, v7
	v_ashrrev_i32_e32 v11, 31, v160
	v_mov_b32_e32 v10, v160
	v_lshl_add_u64 v[142:143], v[10:11], 1, s[16:17]
	v_mad_i64_i32 v[2:3], s[16:17], v13, s54, 0
	s_movk_i32 s16, 0xd0
	s_nop 0
	v_mul_lo_u32 v5, v158, s16
	v_mad_u64_u32 v[148:149], s[16:17], v13, s82, v[0:1]
	v_readlane_b32 s16, v255, 15
	v_and_b32_e32 v0, 7, v8
	s_add_u32 s16, s16, s50
	v_readlane_b32 s17, v255, 16
	v_lshl_or_b32 v2, v0, 4, v2
	s_addc_u32 s17, s17, 0
	v_mov_b32_e32 v149, 0
	v_cmp_lt_i32_e64 s[12:13], 7, v7
	v_lshl_add_u64 v[140:141], v[160:161], 1, s[60:61]
	v_lshl_add_u32 v159, v7, 4, v5
	v_lshl_add_u32 v160, v1, 1, v4
	v_lshl_add_u64 v[150:151], s[16:17], 0, v[2:3]
	v_mov_b32_e32 v33, v149
	v_mov_b32_e32 v34, v149
	v_mov_b32_e32 v35, v149
	v_mov_b32_e32 v36, v149
	v_mov_b32_e32 v37, v149
	v_mov_b32_e32 v38, v149
	v_mov_b32_e32 v39, v149
	v_mov_b32_e32 v40, v149
	v_mov_b32_e32 v41, v149
	v_mov_b32_e32 v42, v149
	v_mov_b32_e32 v43, v149
	v_mov_b32_e32 v44, v149
	v_mov_b32_e32 v45, v149
	v_mov_b32_e32 v46, v149
	v_mov_b32_e32 v47, v149
	v_mov_b32_e32 v0, 0
	v_mov_b32_e32 v1, v149
	v_mov_b32_e32 v2, v149
	v_mov_b32_e32 v3, v149
	v_mov_b32_e32 v4, v149
	v_mov_b32_e32 v5, v149
	v_mov_b32_e32 v6, v149
	v_mov_b32_e32 v7, v149
	v_mov_b32_e32 v8, v149
	v_mov_b32_e32 v9, v149
	v_mov_b32_e32 v10, v149
	v_mov_b32_e32 v11, v149
	v_mov_b32_e32 v12, v149
	v_mov_b32_e32 v13, v149
	v_mov_b32_e32 v14, v149
	v_mov_b32_e32 v15, v149
	v_sub_f32_e32 v16, v16, v162
	v_sub_f32_e32 v17, v17, v162
	v_sub_f32_e32 v18, v18, v162
	v_sub_f32_e32 v19, v19, v162
	v_sub_f32_e32 v20, v20, v162
	v_sub_f32_e32 v21, v21, v162
	v_sub_f32_e32 v22, v22, v162
	v_sub_f32_e32 v23, v23, v162
	v_sub_f32_e32 v24, v24, v162
	v_sub_f32_e32 v25, v25, v162
	v_sub_f32_e32 v26, v26, v162
	v_sub_f32_e32 v27, v27, v162
	v_sub_f32_e32 v28, v28, v162
	v_sub_f32_e32 v29, v29, v162
	v_sub_f32_e32 v30, v30, v162
	v_sub_f32_e32 v31, v31, v162
	v_sub_f32_e32 v64, v64, v162
	v_sub_f32_e32 v65, v65, v162
	v_sub_f32_e32 v66, v66, v162
	v_sub_f32_e32 v67, v67, v162
	v_sub_f32_e32 v68, v68, v162
	v_sub_f32_e32 v69, v69, v162
	v_sub_f32_e32 v70, v70, v162
	v_sub_f32_e32 v71, v71, v162
	v_sub_f32_e32 v72, v72, v162
	v_sub_f32_e32 v73, v73, v162
	v_sub_f32_e32 v74, v74, v162
	v_sub_f32_e32 v75, v75, v162
	v_sub_f32_e32 v76, v76, v162
	v_sub_f32_e32 v77, v77, v162
	v_sub_f32_e32 v78, v78, v162
	v_sub_f32_e32 v79, v79, v162
	v_sub_f32_e32 v164, 0, v162
	v_sub_f32_e32 v165, 0, v162
	v_sub_f32_e32 v166, 0, v162
	v_sub_f32_e32 v167, 0, v162
	v_sub_f32_e32 v168, 0, v162
	v_sub_f32_e32 v169, 0, v162
	v_sub_f32_e32 v170, 0, v162
	v_sub_f32_e32 v171, 0, v162
	v_sub_f32_e32 v172, 0, v162
	v_sub_f32_e32 v173, 0, v162
	v_sub_f32_e32 v174, 0, v162
	v_sub_f32_e32 v175, 0, v162
	v_sub_f32_e32 v176, 0, v162
	v_sub_f32_e32 v177, 0, v162
	v_sub_f32_e32 v178, 0, v162
	v_sub_f32_e32 v179, 0, v162
	s_and_saveexec_b64 s[16:17], s[6:7]
	s_cbranch_execz .Lmpk_c0
	v_add_u32_e32 v124, s38, v158
	v_add_u32_e32 v126, 0x80, v124
	v_ashrrev_i32_e32 v127, 31, v126
	s_and_saveexec_b64 s[72:73], s[12:13]
	s_xor_b64 s[72:73], exec, s[72:73]
	v_lshlrev_b64 v[124:125], 6, v[126:127]
	s_movk_i32 s60, 0xff80
	v_lshl_add_u64 v[124:125], v[140:141], 0, v[124:125]
	s_mov_b32 s61, -1
	v_lshl_add_u64 v[124:125], v[124:125], 0, s[60:61]
	s_andn2_saveexec_b64 s[72:73], s[72:73]
	v_mad_i64_i32 v[124:125], s[74:75], v126, s1, v[142:143]
	s_or_b64 exec, exec, s[72:73]
	global_load_dwordx4 v[124:127], v[124:125], off

.Lmpk_c1:
	s_or_b64 exec, exec, s[16:17]
	s_and_saveexec_b64 s[74:75], s[10:11]
	global_load_dwordx4 v[120:123], v[150:151], off offset:-128
	s_or_b64 exec, exec, s[74:75]
	s_branch .LBB0_543

.LBB0_543:
	s_add_i32 s78, s68, -1
	s_cmp_lt_u32 s78, s34
	s_cselect_b64 s[70:71], -1, 0
	s_cmp_ge_u32 s78, s34
	s_cselect_b64 s[50:51], -1, 0
	s_cmp_ge_u32 s68, s34
	s_cbranch_scc1 .LBB0_557
	s_and_saveexec_b64 s[16:17], s[6:7]
	s_cbranch_execz .Lm1k_c0
	v_add_u32_e32 v220, s38, v158
	v_add_u32_e32 v222, 0xc0, v220
	v_ashrrev_i32_e32 v223, 31, v222
	s_and_saveexec_b64 s[72:73], s[12:13]
	s_xor_b64 s[72:73], exec, s[72:73]
	v_lshlrev_b64 v[220:221], 6, v[222:223]
	s_movk_i32 s60, 0xff80
	v_lshl_add_u64 v[220:221], v[140:141], 0, v[220:221]
	s_mov_b32 s61, -1
	v_lshl_add_u64 v[220:221], v[220:221], 0, s[60:61]
	s_andn2_saveexec_b64 s[72:73], s[72:73]
	v_mad_i64_i32 v[220:221], s[74:75], v222, s1, v[142:143]
	s_or_b64 exec, exec, s[72:73]
	global_load_dwordx4 v[220:223], v[220:221], off
.Lm1k_c0:
	s_or_b64 exec, exec, s[16:17]
	s_and_saveexec_b64 s[16:17], s[8:9]
	s_cbranch_execz .Lm1k_c1
	v_add_u32_e32 v224, s38, v154
	v_add_u32_e32 v226, 0xc0, v224
	v_ashrrev_i32_e32 v227, 31, v226
	s_and_saveexec_b64 s[72:73], s[14:15]
	s_xor_b64 s[72:73], exec, s[72:73]
	v_lshlrev_b64 v[224:225], 6, v[226:227]
	s_movk_i32 s60, 0xff80
	v_lshl_add_u64 v[224:225], v[144:145], 0, v[224:225]
	s_mov_b32 s61, -1
	v_lshl_add_u64 v[224:225], v[224:225], 0, s[60:61]
	s_andn2_saveexec_b64 s[72:73], s[72:73]
	v_mad_i64_i32 v[224:225], s[74:75], v226, s1, v[146:147]
	s_or_b64 exec, exec, s[72:73]
	global_load_dwordx4 v[224:227], v[224:225], off

; template <bool MLA, int DK, int DV>
; __device__ __forceinline__ void attn_core(const Params& p, int b, int h, int map, int q0, int nt, char* smem,
;                                           f32x16 (&o)[DV / 32], float& lout) {
;     ...
;         for (int i = 0; i < 16; ++i) nxt_[sub][i] = 0.f;
;       constexpr int NM = 2 * NKS;
;       bf16x8 kf[NM];
; #pragma unroll
;       for (int j = 0; j < NM; ++j) kf[j] = *(const bf16x8*)(Kn + ((j / NKS) * 32 + r) * KS_STRIDE + (j % NKS) * 16 + h2 * 8);
; #pragma unroll
;       for (int j = 0; j < NM; ++j) {
;         nxt_[j / NKS] = MFMA32(kf[j], qf[j % NKS], nxt_[j / NKS]);
; #pragma unroll
;         for (int e_ = j * 32 / NM; e_ < (j + 1) * 32 / NM; ++e_) {
;           const float x_ = __builtin_amdgcn_exp2f(fmaf(cur_[e_ >> 4][e_ & 15], sc, -mrun));
;           cur_[e_ >> 4][e_ & 15] = x_; psum += x_;
;         }
;       }
;       __builtin_amdgcn_sched_group_barrier(0x100, NM, 0);
; #pragma unroll
;       for (int j = 0; j < NM; ++j) {
;         __builtin_amdgcn_sched_group_barrier(0x008, 1, 0);
;         __builtin_amdgcn_sched_group_barrier(0x002, 96 / NM, 0);
;       }
;     } else {
; #pragma unroll
;       for (int sub = 0; sub < 2; ++sub)
; #pragma unroll
;         for (int i = 0; i < 16; ++i) { const float x_ = __builtin_amdgcn_exp2f(fmaf(cur_[sub][i], sc, -mrun)); cur_[sub][i] = x_; psum += x_; }
;     }
;     lrun += psum;
;     bf16x8 pb[4];
; #pragma unroll
;     for (int kb = 0; kb < 4; ++kb) {
;       const int sub = kb >> 1, s8 = (kb & 1) * 8;
;       u32x4 pk;
;       pk.x = pack2(cur_[sub][s8 + 0], cur_[sub][s8 + 1]);
;       pk.y = pack2(cur_[sub][s8 + 2], cur_[sub][s8 + 3]);
;       pk.z = pack2(cur_[sub][s8 + 4], cur_[sub][s8 + 5]);
;       pk.w = pack2(cur_[sub][s8 + 6], cur_[sub][s8 + 7]);
;       pb[kb] = __builtin_bit_cast(bf16x8, pk);
;     }
;     float mx = -INFINITY;
; #pragma unroll
;     for (int hb = 0; hb < 2; ++hb) {
;       bf16x8 vf[2][NDVT];
; #pragma unroll
;       for (int q = 0; q < 2; ++q)
; #pragma unroll
;         for (int d = 0; d < NDVT; ++d) {
;           const bft* vp = Vc + (d * 32 + r) * VS_STRIDE + (hb * 2 + q) * 16 + 4 * h2;
;           const u32x2 lo = *(const u32x2*)vp, hi = *(const u32x2*)(vp + 8);
;           const u32x4 pa4 = {lo.x, lo.y, hi.x, hi.y};
;           vf[q][d] = __builtin_bit_cast(bf16x8, pa4);
;         }
; #pragma unroll
.LBB0_557:
	s_add_i32 s72, s68, -2
	s_cmp_lt_u32 s72, s34
	s_cselect_b64 s[16:17], -1, 0
	s_cmp_ge_u32 s72, s34
	s_cselect_b64 s[76:77], -1, 0
	s_and_b64 s[72:73], s[10:11], s[16:17]
	s_and_b64 vcc, s[10:11], s[70:71]
	s_and_saveexec_b64 s[74:75], vcc
	s_cbranch_execz .LBB0_559
	global_load_dwordx4 v[228:231], v[150:151], off
.LBB0_559:
	s_or_b64 exec, exec, s[74:75]
	s_and_b64 vcc, exec, s[76:77]
	s_cbranch_vccnz .Lmla1_cold
	ds_read_b128 v[132:135], v155 offset:13312
	ds_read_b128 v[136:139], v155 offset:13344
	ds_read_b128 v[198:201], v155 offset:13376
	ds_read_b128 v[202:205], v155 offset:13408
	ds_read_b128 v[248:251], v155 offset:13440
	ds_read_b128 v[216:219], v155 offset:13472
	v_add_u32_e32 v244, 0x6800, v157
	v_add_u32_e32 v245, 0x7800, v157
	v_exp_f32_e32 v16, v16
	v_exp_f32_e32 v17, v17
	v_exp_f32_e32 v18, v18
	v_exp_f32_e32 v19, v19
	v_add_f32_e32 v163, v16, v18
	v_add_f32_e32 v210, v17, v19
	s_waitcnt lgkmcnt(5)
	v_mfma_f32_32x32x16_bf16 v[48:63], v[132:135], v[96:99], v[164:179]
	ds_read_b128 v[132:135], v155 offset:19968
	v_exp_f32_e32 v20, v20
	v_exp_f32_e32 v21, v21
	v_exp_f32_e32 v22, v22
	s_waitcnt lgkmcnt(5)
	v_mfma_f32_32x32x16_bf16 v[48:63], v[136:139], v[100:103], v[48:63]
	ds_read_b128 v[136:139], v155 offset:20000
	v_exp_f32_e32 v23, v23
	v_add_f32_e32 v163, v20, v163
	v_add_f32_e32 v210, v21, v210
	s_waitcnt lgkmcnt(5)
	v_mfma_f32_32x32x16_bf16 v[48:63], v[198:201], v[104:107], v[48:63]
	ds_read_b128 v[198:201], v155 offset:20032
	v_add_f32_e32 v163, v22, v163
	v_add_f32_e32 v210, v23, v210
	v_cvt_pk_bf16_f32 v180, v16, v17
	v_cvt_pk_bf16_f32 v181, v18, v19
	v_cvt_pk_bf16_f32 v182, v20, v21
	s_waitcnt lgkmcnt(5)
	v_mfma_f32_32x32x16_bf16 v[48:63], v[202:205], v[108:111], v[48:63]
	ds_read_b128 v[202:205], v155 offset:20064
	v_cvt_pk_bf16_f32 v183, v22, v23
	v_exp_f32_e32 v24, v24
	v_exp_f32_e32 v25, v25
	s_waitcnt lgkmcnt(5)
	v_mfma_f32_32x32x16_bf16 v[48:63], v[248:251], v[112:115], v[48:63]
	ds_read_b128 v[248:251], v155 offset:20096
	v_exp_f32_e32 v26, v26
	v_exp_f32_e32 v27, v27
	v_add_f32_e32 v163, v24, v163
	s_waitcnt lgkmcnt(5)
	v_mfma_f32_32x32x16_bf16 v[48:63], v[216:219], v[116:119], v[48:63]
	ds_read_b128 v[216:219], v155 offset:20128
	v_add_f32_e32 v210, v25, v210
	v_add_f32_e32 v163, v26, v163
	v_add_f32_e32 v210, v27, v210
	v_exp_f32_e32 v28, v28
	s_waitcnt lgkmcnt(5)
	v_mfma_f32_32x32x16_bf16 v[80:95], v[132:135], v[96:99], v[164:179]
	ds_read2_b64 v[132:135], v244 offset0:0 offset1:2
	v_exp_f32_e32 v29, v29
	v_exp_f32_e32 v30, v30
	v_exp_f32_e32 v31, v31
	s_waitcnt lgkmcnt(5)
	v_mfma_f32_32x32x16_bf16 v[80:95], v[136:139], v[100:103], v[80:95]
	ds_read2_b64 v[136:139], v245 offset0:32 offset1:34
	v_add_f32_e32 v163, v28, v163
	v_add_f32_e32 v210, v29, v210
	v_add_f32_e32 v163, v30, v163
	v_add_f32_e32 v210, v31, v210
	s_waitcnt lgkmcnt(5)
	v_mfma_f32_32x32x16_bf16 v[80:95], v[198:201], v[104:107], v[80:95]
	ds_read2_b64 v[198:201], v244 offset0:4 offset1:6
	v_cvt_pk_bf16_f32 v184, v24, v25
	v_cvt_pk_bf16_f32 v185, v26, v27
	v_cvt_pk_bf16_f32 v186, v28, v29
	v_cvt_pk_bf16_f32 v187, v30, v31
	v_exp_f32_e32 v64, v64
	s_waitcnt lgkmcnt(5)
	v_mfma_f32_32x32x16_bf16 v[80:95], v[202:205], v[108:111], v[80:95]
	ds_read2_b64 v[202:205], v245 offset0:36 offset1:38
	v_exp_f32_e32 v65, v65
	v_exp_f32_e32 v66, v66
	s_waitcnt lgkmcnt(5)
	v_mfma_f32_32x32x16_bf16 v[80:95], v[248:251], v[112:115], v[80:95]
	ds_read2_b64 v[248:251], v244 offset0:8 offset1:10
	v_exp_f32_e32 v67, v67
	v_add_f32_e32 v163, v64, v163
	v_add_f32_e32 v210, v65, v210
	s_waitcnt lgkmcnt(5)
	v_mfma_f32_32x32x16_bf16 v[80:95], v[216:219], v[116:119], v[80:95]
	ds_read2_b64 v[216:219], v245 offset0:40 offset1:42
	v_add_f32_e32 v163, v66, v163
	v_add_f32_e32 v210, v67, v210
	v_exp_f32_e32 v68, v68
	v_exp_f32_e32 v69, v69
	s_waitcnt lgkmcnt(5)
	v_mfma_f32_32x32x16_bf16 v[32:47], v[132:135], v[180:183], v[32:47]
	ds_read2_b64 v[132:135], v244 offset0:12 offset1:14
	v_exp_f32_e32 v70, v70
	v_exp_f32_e32 v71, v71
	s_waitcnt lgkmcnt(5)
	v_mfma_f32_32x32x16_bf16 v[0:15], v[136:139], v[180:183], v[0:15]
	ds_read2_b64 v[136:139], v245 offset0:44 offset1:46
	v_add_f32_e32 v163, v68, v163
	v_add_f32_e32 v210, v69, v210
	v_add_f32_e32 v163, v70, v163
	v_add_f32_e32 v210, v71, v210
	v_cvt_pk_bf16_f32 v188, v64, v65
	s_waitcnt lgkmcnt(5)
	v_mfma_f32_32x32x16_bf16 v[32:47], v[198:201], v[184:187], v[32:47]
	v_cvt_pk_bf16_f32 v189, v66, v67
	v_cvt_pk_bf16_f32 v190, v68, v69
	v_cvt_pk_bf16_f32 v191, v70, v71
	v_exp_f32_e32 v72, v72
	s_waitcnt lgkmcnt(4)
	v_mfma_f32_32x32x16_bf16 v[0:15], v[202:205], v[184:187], v[0:15]
	v_exp_f32_e32 v73, v73
	v_exp_f32_e32 v74, v74
	v_exp_f32_e32 v75, v75
	s_waitcnt lgkmcnt(3)
	v_mfma_f32_32x32x16_bf16 v[32:47], v[248:251], v[188:191], v[32:47]
	v_add_f32_e32 v163, v72, v163
	v_add_f32_e32 v210, v73, v210
	v_add_f32_e32 v163, v74, v163
	v_add_f32_e32 v210, v75, v210
	s_waitcnt lgkmcnt(2)
	v_mfma_f32_32x32x16_bf16 v[0:15], v[216:219], v[188:191], v[0:15]
	v_exp_f32_e32 v76, v76
	v_exp_f32_e32 v77, v77
	v_exp_f32_e32 v78, v78
	v_exp_f32_e32 v79, v79
	v_add_f32_e32 v163, v76, v163
	v_add_f32_e32 v210, v77, v210
	v_add_f32_e32 v163, v78, v163
	v_add_f32_e32 v210, v79, v210
	v_cvt_pk_bf16_f32 v192, v72, v73
	v_cvt_pk_bf16_f32 v193, v74, v75
	v_cvt_pk_bf16_f32 v194, v76, v77
	v_cvt_pk_bf16_f32 v195, v78, v79
	s_waitcnt lgkmcnt(1)
	s_nop 0
	v_mfma_f32_32x32x16_bf16 v[32:47], v[132:135], v[192:195], v[32:47]
	s_waitcnt lgkmcnt(0)
	v_mfma_f32_32x32x16_bf16 v[0:15], v[136:139], v[192:195], v[0:15]
	v_add_f32_e32 v163, v163, v210
	v_add_f32_e32 v149, v149, v163
	v_cmp_lt_f32_e32 vcc, 0x45800000, v163
	s_cbranch_vccz .LBB0_566
; template <bool MLA, int DK, int DV>
; __device__ __forceinline__ void attn_core(const Params& p, int b, int h, int map, int q0, int nt, char* smem,
;                                           f32x16 (&o)[DV / 32], float& lout) {
;     ...
;     if (has1) {
;       mx *= sc;
;       if (__any(mx > mrun + 12.f)) {
;         mx = fmaxf(mx, __shfl_xor(mx, 32));
;         const float mnew = fmaxf(mrun, mx);
;         const float alpha = __builtin_amdgcn_exp2f(mrun - mnew);
;         mrun = mnew;
;         lrun *= alpha;
; #pragma unroll
;         for (int d = 0; d < NDVT; ++d)
; #pragma unroll
;           for (int i = 0; i < 16; ++i) o[d][i] *= alpha;
;       }
	v_max3_f32 v163, v16, v17, v18
	v_max3_f32 v163, v163, v19, v20
	v_max3_f32 v163, v163, v21, v22
	v_max3_f32 v163, v163, v23, v24
	v_max3_f32 v163, v163, v25, v26
	v_max3_f32 v163, v163, v27, v28
	v_max3_f32 v163, v163, v29, v30
	v_max3_f32 v163, v163, v31, v64
	v_max3_f32 v163, v163, v65, v66
	v_max3_f32 v163, v163, v67, v68
	v_max3_f32 v163, v163, v69, v70
	v_max3_f32 v163, v163, v71, v72
	v_max3_f32 v163, v163, v73, v74
	v_max3_f32 v163, v163, v75, v76
	v_max3_f32 v163, v163, v77, v78
	v_max_f32_e32 v163, v163, v79
	ds_bpermute_b32 v210, v156, v163
	s_waitcnt lgkmcnt(0)
	v_max_f32_e32 v163, v163, v210
	v_frexp_exp_i32_f32_e32 v210, v163
	v_max_i32_e32 v210, 0, v210
	v_sub_u32_e32 v247, 0, v210
	v_ldexp_f32 v247, 1.0, v247
	v_cvt_f32_i32_e32 v210, v210
	v_mul_f32_e32 v149, v149, v247
	v_mul_f32_e32 v32, v32, v247
	v_mul_f32_e32 v33, v33, v247
	v_mul_f32_e32 v34, v34, v247
	v_mul_f32_e32 v35, v35, v247
	v_mul_f32_e32 v36, v36, v247
	v_mul_f32_e32 v37, v37, v247
	v_mul_f32_e32 v38, v38, v247
	v_mul_f32_e32 v39, v39, v247
	v_mul_f32_e32 v40, v40, v247
	v_mul_f32_e32 v41, v41, v247
	v_mul_f32_e32 v42, v42, v247
	v_mul_f32_e32 v43, v43, v247
	v_mul_f32_e32 v44, v44, v247
	v_mul_f32_e32 v45, v45, v247
	v_mul_f32_e32 v46, v46, v247
	v_mul_f32_e32 v47, v47, v247
	v_mul_f32_e32 v0, v0, v247
	v_mul_f32_e32 v1, v1, v247
	v_mul_f32_e32 v2, v2, v247
	v_mul_f32_e32 v3, v3, v247
	v_mul_f32_e32 v4, v4, v247
	v_mul_f32_e32 v5, v5, v247
	v_mul_f32_e32 v6, v6, v247
	v_mul_f32_e32 v7, v7, v247
	v_mul_f32_e32 v8, v8, v247
	v_mul_f32_e32 v9, v9, v247
	v_mul_f32_e32 v10, v10, v247
	v_mul_f32_e32 v11, v11, v247
	v_mul_f32_e32 v12, v12, v247
	v_mul_f32_e32 v13, v13, v247
	v_mul_f32_e32 v14, v14, v247
	v_mul_f32_e32 v15, v15, v247
	v_sub_f32_e32 v164, v164, v210
	v_sub_f32_e32 v165, v165, v210
	v_sub_f32_e32 v166, v166, v210
	v_sub_f32_e32 v167, v167, v210
	v_sub_f32_e32 v168, v168, v210
	v_sub_f32_e32 v169, v169, v210
	v_sub_f32_e32 v170, v170, v210
	v_sub_f32_e32 v171, v171, v210
	v_sub_f32_e32 v172, v172, v210
	v_sub_f32_e32 v173, v173, v210
	v_sub_f32_e32 v174, v174, v210
	v_sub_f32_e32 v175, v175, v210
	v_sub_f32_e32 v176, v176, v210
	v_sub_f32_e32 v177, v177, v210
	v_sub_f32_e32 v178, v178, v210
	v_sub_f32_e32 v179, v179, v210
	v_sub_f32_e32 v48, v48, v210
	v_sub_f32_e32 v49, v49, v210
	v_sub_f32_e32 v50, v50, v210
	v_sub_f32_e32 v51, v51, v210
	v_sub_f32_e32 v52, v52, v210
	v_sub_f32_e32 v53, v53, v210
	v_sub_f32_e32 v54, v54, v210
	v_sub_f32_e32 v55, v55, v210
	v_sub_f32_e32 v56, v56, v210
	v_sub_f32_e32 v57, v57, v210
	v_sub_f32_e32 v58, v58, v210
	v_sub_f32_e32 v59, v59, v210
	v_sub_f32_e32 v60, v60, v210
	v_sub_f32_e32 v61, v61, v210
	v_sub_f32_e32 v62, v62, v210
	v_sub_f32_e32 v63, v63, v210
	v_sub_f32_e32 v80, v80, v210
	v_sub_f32_e32 v81, v81, v210
	v_sub_f32_e32 v82, v82, v210
	v_sub_f32_e32 v83, v83, v210
	v_sub_f32_e32 v84, v84, v210
	v_sub_f32_e32 v85, v85, v210
	v_sub_f32_e32 v86, v86, v210
	v_sub_f32_e32 v87, v87, v210
	v_sub_f32_e32 v88, v88, v210
	v_sub_f32_e32 v89, v89, v210
	v_sub_f32_e32 v90, v90, v210
	v_sub_f32_e32 v91, v91, v210
	v_sub_f32_e32 v92, v92, v210
	v_sub_f32_e32 v93, v93, v210
	v_sub_f32_e32 v94, v94, v210
	v_sub_f32_e32 v95, v95, v210
	v_add_f32_e32 v162, v162, v210
	s_branch .LBB0_566

; template <bool MLA, int DK, int DV>
; __device__ __forceinline__ void attn_core(const Params& p, int b, int h, int map, int q0, int nt, char* smem,
;                                           f32x16 (&o)[DV / 32], float& lout) {
;     ...
;     if (has2) ATTN_STOREK(kt & 1);
;     if (has1) ATTN_STOREV((kt + 1) & 1);
.LBB0_566:
	s_cmp_lt_u32 s68, s34
	s_cbranch_scc0 .Lm1w_ns
	s_and_b64 vcc, exec, s[8:9]
	s_cbranch_vccnz .Lm1w_w3
	s_waitcnt vmcnt(2)
	s_branch .Lm1w_wd
.Lm1w_w3:
	s_waitcnt vmcnt(3)
	s_branch .Lm1w_wd

.Lm1w_wd:
	v_cndmask_b32_e64 v132, 0, 1, s[70:71]
	v_cmp_ne_u32_e64 s[16:17], 1, v132
	s_andn2_b64 vcc, exec, s[70:71]
	s_cbranch_vccnz .LBB0_572
	s_and_saveexec_b64 s[74:75], s[6:7]
	s_cbranch_execz .LBB0_569
	ds_write_b128 v159, v[124:127]
.LBB0_569:
	s_or_b64 exec, exec, s[74:75]
	s_and_saveexec_b64 s[74:75], s[8:9]
	s_cbranch_execz .LBB0_571
	ds_write_b128 v160, v[128:131]

.LBB0_572:
	s_and_saveexec_b64 s[74:75], s[72:73]
	s_cbranch_execz .LBB0_574
	v_add_u32_e32 v132, 0x8a00, v148
	ds_write2_b64 v132, v[120:121], v[122:123] offset1:1
.LBB0_574:
	s_or_b64 exec, exec, s[74:75]
	s_cmp_lt_u32 s68, s34
	s_cselect_b64 s[72:73], -1, 0
	s_add_i32 s60, s68, 1
	s_cmp_ge_u32 s60, s34
	s_waitcnt lgkmcnt(0)
	s_barrier
	s_cbranch_scc1 .LBB0_588
	s_and_saveexec_b64 s[74:75], s[6:7]
	s_cbranch_execz .Lm2k_c0
	v_add_u32_e32 v124, s38, v158
	v_add_u32_e32 v126, 0x100, v124
	v_ashrrev_i32_e32 v127, 31, v126
	s_and_saveexec_b64 s[76:77], s[12:13]
	s_xor_b64 s[76:77], exec, s[76:77]
	v_lshlrev_b64 v[124:125], 6, v[126:127]
	s_movk_i32 s60, 0xff80
	v_lshl_add_u64 v[124:125], v[140:141], 0, v[124:125]
	s_mov_b32 s61, -1
	v_lshl_add_u64 v[124:125], v[124:125], 0, s[60:61]
	s_andn2_saveexec_b64 s[76:77], s[76:77]
	v_mad_i64_i32 v[124:125], s[80:81], v126, s1, v[142:143]
	s_or_b64 exec, exec, s[76:77]
	global_load_dwordx4 v[124:127], v[124:125], off
.Lm2k_c0:
	s_or_b64 exec, exec, s[74:75]
	s_and_saveexec_b64 s[74:75], s[8:9]
	s_cbranch_execz .Lm2k_c1
	v_add_u32_e32 v128, s38, v154
	v_add_u32_e32 v130, 0x100, v128
	v_ashrrev_i32_e32 v131, 31, v130
	s_and_saveexec_b64 s[76:77], s[14:15]
	s_xor_b64 s[76:77], exec, s[76:77]
	v_lshlrev_b64 v[128:129], 6, v[130:131]
	s_movk_i32 s60, 0xff80
	v_lshl_add_u64 v[128:129], v[144:145], 0, v[128:129]
	s_mov_b32 s61, -1
	v_lshl_add_u64 v[128:129], v[128:129], 0, s[60:61]
	s_andn2_saveexec_b64 s[76:77], s[76:77]
	v_mad_i64_i32 v[128:129], s[80:81], v130, s1, v[146:147]
	s_or_b64 exec, exec, s[76:77]
	global_load_dwordx4 v[128:131], v[128:129], off

; template <bool MLA, int DK, int DV>
; __device__ __forceinline__ void attn_core(const Params& p, int b, int h, int map, int q0, int nt, char* smem,
;                                           f32x16 (&o)[DV / 32], float& lout) {
;     ...
;         for (int i = 0; i < 16; ++i) nxt_[sub][i] = 0.f;
;       constexpr int NM = 2 * NKS;
;       bf16x8 kf[NM];
; #pragma unroll
;       for (int j = 0; j < NM; ++j) kf[j] = *(const bf16x8*)(Kn + ((j / NKS) * 32 + r) * KS_STRIDE + (j % NKS) * 16 + h2 * 8);
; #pragma unroll
;       for (int j = 0; j < NM; ++j) {
;         nxt_[j / NKS] = MFMA32(kf[j], qf[j % NKS], nxt_[j / NKS]);
; #pragma unroll
;         for (int e_ = j * 32 / NM; e_ < (j + 1) * 32 / NM; ++e_) {
;           const float x_ = __builtin_amdgcn_exp2f(fmaf(cur_[e_ >> 4][e_ & 15], sc, -mrun));
;           cur_[e_ >> 4][e_ & 15] = x_; psum += x_;
;         }
;       }
;       __builtin_amdgcn_sched_group_barrier(0x100, NM, 0);
; #pragma unroll
;       for (int j = 0; j < NM; ++j) {
;         __builtin_amdgcn_sched_group_barrier(0x008, 1, 0);
;         __builtin_amdgcn_sched_group_barrier(0x002, 96 / NM, 0);
;       }
;     } else {
; #pragma unroll
;       for (int sub = 0; sub < 2; ++sub)
; #pragma unroll
;         for (int i = 0; i < 16; ++i) { const float x_ = __builtin_amdgcn_exp2f(fmaf(cur_[sub][i], sc, -mrun)); cur_[sub][i] = x_; psum += x_; }
;     }
;     lrun += psum;
;     bf16x8 pb[4];
; #pragma unroll
;     for (int kb = 0; kb < 4; ++kb) {
;       const int sub = kb >> 1, s8 = (kb & 1) * 8;
;       u32x4 pk;
;       pk.x = pack2(cur_[sub][s8 + 0], cur_[sub][s8 + 1]);
;       pk.y = pack2(cur_[sub][s8 + 2], cur_[sub][s8 + 3]);
;       pk.z = pack2(cur_[sub][s8 + 4], cur_[sub][s8 + 5]);
;       pk.w = pack2(cur_[sub][s8 + 6], cur_[sub][s8 + 7]);
;       pb[kb] = __builtin_bit_cast(bf16x8, pk);
;     }
;     float mx = -INFINITY;
; #pragma unroll
;     for (int hb = 0; hb < 2; ++hb) {
;       bf16x8 vf[2][NDVT];
; #pragma unroll
;       for (int q = 0; q < 2; ++q)
; #pragma unroll
;         for (int d = 0; d < NDVT; ++d) {
;           const bft* vp = Vc + (d * 32 + r) * VS_STRIDE + (hb * 2 + q) * 16 + 4 * h2;
;           const u32x2 lo = *(const u32x2*)vp, hi = *(const u32x2*)(vp + 8);
;           const u32x4 pa4 = {lo.x, lo.y, hi.x, hi.y};
;           vf[q][d] = __builtin_bit_cast(bf16x8, pa4);
;         }
; #pragma unroll
.LBB0_588:
	s_and_b64 s[70:71], s[10:11], s[70:71]
	s_and_b64 vcc, s[10:11], s[72:73]
	s_and_saveexec_b64 s[74:75], vcc
	s_cbranch_execz .LBB0_590
	global_load_dwordx4 v[120:123], v[150:151], off offset:128
.LBB0_590:
	s_or_b64 exec, exec, s[74:75]
	s_and_b64 vcc, exec, s[50:51]
	s_cbranch_vccnz .Lmla2_cold
	ds_read_b128 v[132:135], v155 offset:0
	ds_read_b128 v[136:139], v155 offset:32
	ds_read_b128 v[198:201], v155 offset:64
	ds_read_b128 v[202:205], v155 offset:96
	ds_read_b128 v[248:251], v155 offset:128
	ds_read_b128 v[216:219], v155 offset:160
	v_add_u32_e32 v244, 0x8800, v157
	v_add_u32_e32 v245, 0x9800, v157
	v_exp_f32_e32 v48, v48
	v_exp_f32_e32 v49, v49
	v_exp_f32_e32 v50, v50
	v_exp_f32_e32 v51, v51
	v_add_f32_e32 v163, v48, v50
	v_add_f32_e32 v210, v49, v51
	s_waitcnt lgkmcnt(5)
	v_mfma_f32_32x32x16_bf16 v[16:31], v[132:135], v[96:99], v[164:179]
	ds_read_b128 v[132:135], v155 offset:6656
	v_exp_f32_e32 v52, v52
	v_exp_f32_e32 v53, v53
	v_exp_f32_e32 v54, v54
	s_waitcnt lgkmcnt(5)
	v_mfma_f32_32x32x16_bf16 v[16:31], v[136:139], v[100:103], v[16:31]
	ds_read_b128 v[136:139], v155 offset:6688
	v_exp_f32_e32 v55, v55
	v_add_f32_e32 v163, v52, v163
	v_add_f32_e32 v210, v53, v210
	s_waitcnt lgkmcnt(5)
	v_mfma_f32_32x32x16_bf16 v[16:31], v[198:201], v[104:107], v[16:31]
	ds_read_b128 v[198:201], v155 offset:6720
	v_add_f32_e32 v163, v54, v163
	v_add_f32_e32 v210, v55, v210
	v_cvt_pk_bf16_f32 v180, v48, v49
	v_cvt_pk_bf16_f32 v181, v50, v51
	v_cvt_pk_bf16_f32 v182, v52, v53
	s_waitcnt lgkmcnt(5)
	v_mfma_f32_32x32x16_bf16 v[16:31], v[202:205], v[108:111], v[16:31]
	ds_read_b128 v[202:205], v155 offset:6752
	v_cvt_pk_bf16_f32 v183, v54, v55
	v_exp_f32_e32 v56, v56
	v_exp_f32_e32 v57, v57
	s_waitcnt lgkmcnt(5)
	v_mfma_f32_32x32x16_bf16 v[16:31], v[248:251], v[112:115], v[16:31]
	ds_read_b128 v[248:251], v155 offset:6784
	v_exp_f32_e32 v58, v58
	v_exp_f32_e32 v59, v59
	v_add_f32_e32 v163, v56, v163
	s_waitcnt lgkmcnt(5)
	v_mfma_f32_32x32x16_bf16 v[16:31], v[216:219], v[116:119], v[16:31]
	ds_read_b128 v[216:219], v155 offset:6816
	v_add_f32_e32 v210, v57, v210
	v_add_f32_e32 v163, v58, v163
	v_add_f32_e32 v210, v59, v210
	v_exp_f32_e32 v60, v60
	s_waitcnt lgkmcnt(5)
	v_mfma_f32_32x32x16_bf16 v[64:79], v[132:135], v[96:99], v[164:179]
	ds_read2_b64 v[132:135], v244 offset0:64 offset1:66
	v_exp_f32_e32 v61, v61
	v_exp_f32_e32 v62, v62
	v_exp_f32_e32 v63, v63
	s_waitcnt lgkmcnt(5)
	v_mfma_f32_32x32x16_bf16 v[64:79], v[136:139], v[100:103], v[64:79]
	ds_read2_b64 v[136:139], v245 offset0:96 offset1:98
	v_add_f32_e32 v163, v60, v163
	v_add_f32_e32 v210, v61, v210
	v_add_f32_e32 v163, v62, v163
	v_add_f32_e32 v210, v63, v210
	s_waitcnt lgkmcnt(5)
	v_mfma_f32_32x32x16_bf16 v[64:79], v[198:201], v[104:107], v[64:79]
	ds_read2_b64 v[198:201], v244 offset0:68 offset1:70
	v_cvt_pk_bf16_f32 v184, v56, v57
	v_cvt_pk_bf16_f32 v185, v58, v59
	v_cvt_pk_bf16_f32 v186, v60, v61
	v_cvt_pk_bf16_f32 v187, v62, v63
	v_exp_f32_e32 v80, v80
	s_waitcnt lgkmcnt(5)
	v_mfma_f32_32x32x16_bf16 v[64:79], v[202:205], v[108:111], v[64:79]
	ds_read2_b64 v[202:205], v245 offset0:100 offset1:102
	v_exp_f32_e32 v81, v81
	v_exp_f32_e32 v82, v82
	s_waitcnt lgkmcnt(5)
	v_mfma_f32_32x32x16_bf16 v[64:79], v[248:251], v[112:115], v[64:79]
	ds_read2_b64 v[248:251], v244 offset0:72 offset1:74
	v_exp_f32_e32 v83, v83
	v_add_f32_e32 v163, v80, v163
	v_add_f32_e32 v210, v81, v210
	s_waitcnt lgkmcnt(5)
	v_mfma_f32_32x32x16_bf16 v[64:79], v[216:219], v[116:119], v[64:79]
	ds_read2_b64 v[216:219], v245 offset0:104 offset1:106
	v_add_f32_e32 v163, v82, v163
	v_add_f32_e32 v210, v83, v210
	v_exp_f32_e32 v84, v84
	v_exp_f32_e32 v85, v85
	s_waitcnt lgkmcnt(5)
	v_mfma_f32_32x32x16_bf16 v[32:47], v[132:135], v[180:183], v[32:47]
	ds_read2_b64 v[132:135], v244 offset0:76 offset1:78
	v_exp_f32_e32 v86, v86
	v_exp_f32_e32 v87, v87
	s_waitcnt lgkmcnt(5)
	v_mfma_f32_32x32x16_bf16 v[0:15], v[136:139], v[180:183], v[0:15]
	ds_read2_b64 v[136:139], v245 offset0:108 offset1:110
	v_add_f32_e32 v163, v84, v163
	v_add_f32_e32 v210, v85, v210
	v_add_f32_e32 v163, v86, v163
	v_add_f32_e32 v210, v87, v210
	v_cvt_pk_bf16_f32 v188, v80, v81
	s_waitcnt lgkmcnt(5)
	v_mfma_f32_32x32x16_bf16 v[32:47], v[198:201], v[184:187], v[32:47]
	v_cvt_pk_bf16_f32 v189, v82, v83
	v_cvt_pk_bf16_f32 v190, v84, v85
	v_cvt_pk_bf16_f32 v191, v86, v87
	v_exp_f32_e32 v88, v88
	s_waitcnt lgkmcnt(4)
	v_mfma_f32_32x32x16_bf16 v[0:15], v[202:205], v[184:187], v[0:15]
	v_exp_f32_e32 v89, v89
	v_exp_f32_e32 v90, v90
	v_exp_f32_e32 v91, v91
	s_waitcnt lgkmcnt(3)
	v_mfma_f32_32x32x16_bf16 v[32:47], v[248:251], v[188:191], v[32:47]
	v_add_f32_e32 v163, v88, v163
	v_add_f32_e32 v210, v89, v210
	v_add_f32_e32 v163, v90, v163
	v_add_f32_e32 v210, v91, v210
	s_waitcnt lgkmcnt(2)
	v_mfma_f32_32x32x16_bf16 v[0:15], v[216:219], v[188:191], v[0:15]
	v_exp_f32_e32 v92, v92
	v_exp_f32_e32 v93, v93
	v_exp_f32_e32 v94, v94
	v_exp_f32_e32 v95, v95
	v_add_f32_e32 v163, v92, v163
	v_add_f32_e32 v210, v93, v210
	v_add_f32_e32 v163, v94, v163
	v_add_f32_e32 v210, v95, v210
	v_cvt_pk_bf16_f32 v192, v88, v89
	v_cvt_pk_bf16_f32 v193, v90, v91
	v_cvt_pk_bf16_f32 v194, v92, v93
	v_cvt_pk_bf16_f32 v195, v94, v95
	s_waitcnt lgkmcnt(1)
	s_nop 0
	v_mfma_f32_32x32x16_bf16 v[32:47], v[132:135], v[192:195], v[32:47]
	s_waitcnt lgkmcnt(0)
	v_mfma_f32_32x32x16_bf16 v[0:15], v[136:139], v[192:195], v[0:15]
	v_add_f32_e32 v163, v163, v210
	v_add_f32_e32 v149, v149, v163
	v_cmp_lt_f32_e32 vcc, 0x45800000, v163
	s_cbranch_vccz .LBB0_597
; template <bool MLA, int DK, int DV>
; __device__ __forceinline__ void attn_core(const Params& p, int b, int h, int map, int q0, int nt, char* smem,
;                                           f32x16 (&o)[DV / 32], float& lout) {
;     ...
;     if (has1) {
;       mx *= sc;
;       if (__any(mx > mrun + 12.f)) {
;         mx = fmaxf(mx, __shfl_xor(mx, 32));
;         const float mnew = fmaxf(mrun, mx);
;         const float alpha = __builtin_amdgcn_exp2f(mrun - mnew);
;         mrun = mnew;
;         lrun *= alpha;
; #pragma unroll
;         for (int d = 0; d < NDVT; ++d)
; #pragma unroll
;           for (int i = 0; i < 16; ++i) o[d][i] *= alpha;
;       }
	v_max3_f32 v163, v48, v49, v50
	v_max3_f32 v163, v163, v51, v52
	v_max3_f32 v163, v163, v53, v54
	v_max3_f32 v163, v163, v55, v56
	v_max3_f32 v163, v163, v57, v58
	v_max3_f32 v163, v163, v59, v60
	v_max3_f32 v163, v163, v61, v62
	v_max3_f32 v163, v163, v63, v80
	v_max3_f32 v163, v163, v81, v82
	v_max3_f32 v163, v163, v83, v84
	v_max3_f32 v163, v163, v85, v86
	v_max3_f32 v163, v163, v87, v88
	v_max3_f32 v163, v163, v89, v90
	v_max3_f32 v163, v163, v91, v92
	v_max3_f32 v163, v163, v93, v94
	v_max_f32_e32 v163, v163, v95
	ds_bpermute_b32 v210, v156, v163
	s_waitcnt lgkmcnt(0)
	v_max_f32_e32 v163, v163, v210
	v_frexp_exp_i32_f32_e32 v210, v163
	v_max_i32_e32 v210, 0, v210
	v_sub_u32_e32 v247, 0, v210
	v_ldexp_f32 v247, 1.0, v247
	v_cvt_f32_i32_e32 v210, v210
	v_mul_f32_e32 v149, v149, v247
	v_mul_f32_e32 v32, v32, v247
	v_mul_f32_e32 v33, v33, v247
	v_mul_f32_e32 v34, v34, v247
	v_mul_f32_e32 v35, v35, v247
	v_mul_f32_e32 v36, v36, v247
	v_mul_f32_e32 v37, v37, v247
	v_mul_f32_e32 v38, v38, v247
	v_mul_f32_e32 v39, v39, v247
	v_mul_f32_e32 v40, v40, v247
	v_mul_f32_e32 v41, v41, v247
	v_mul_f32_e32 v42, v42, v247
	v_mul_f32_e32 v43, v43, v247
	v_mul_f32_e32 v44, v44, v247
	v_mul_f32_e32 v45, v45, v247
	v_mul_f32_e32 v46, v46, v247
	v_mul_f32_e32 v47, v47, v247
	v_mul_f32_e32 v0, v0, v247
	v_mul_f32_e32 v1, v1, v247
	v_mul_f32_e32 v2, v2, v247
	v_mul_f32_e32 v3, v3, v247
	v_mul_f32_e32 v4, v4, v247
	v_mul_f32_e32 v5, v5, v247
	v_mul_f32_e32 v6, v6, v247
	v_mul_f32_e32 v7, v7, v247
	v_mul_f32_e32 v8, v8, v247
	v_mul_f32_e32 v9, v9, v247
	v_mul_f32_e32 v10, v10, v247
	v_mul_f32_e32 v11, v11, v247
	v_mul_f32_e32 v12, v12, v247
	v_mul_f32_e32 v13, v13, v247
	v_mul_f32_e32 v14, v14, v247
	v_mul_f32_e32 v15, v15, v247
	v_sub_f32_e32 v164, v164, v210
	v_sub_f32_e32 v165, v165, v210
	v_sub_f32_e32 v166, v166, v210
	v_sub_f32_e32 v167, v167, v210
	v_sub_f32_e32 v168, v168, v210
	v_sub_f32_e32 v169, v169, v210
	v_sub_f32_e32 v170, v170, v210
	v_sub_f32_e32 v171, v171, v210
	v_sub_f32_e32 v172, v172, v210
	v_sub_f32_e32 v173, v173, v210
	v_sub_f32_e32 v174, v174, v210
	v_sub_f32_e32 v175, v175, v210
	v_sub_f32_e32 v176, v176, v210
	v_sub_f32_e32 v177, v177, v210
	v_sub_f32_e32 v178, v178, v210
	v_sub_f32_e32 v179, v179, v210
	v_sub_f32_e32 v16, v16, v210
	v_sub_f32_e32 v17, v17, v210
	v_sub_f32_e32 v18, v18, v210
	v_sub_f32_e32 v19, v19, v210
	v_sub_f32_e32 v20, v20, v210
	v_sub_f32_e32 v21, v21, v210
	v_sub_f32_e32 v22, v22, v210
	v_sub_f32_e32 v23, v23, v210
	v_sub_f32_e32 v24, v24, v210
	v_sub_f32_e32 v25, v25, v210
	v_sub_f32_e32 v26, v26, v210
	v_sub_f32_e32 v27, v27, v210
	v_sub_f32_e32 v28, v28, v210
	v_sub_f32_e32 v29, v29, v210
	v_sub_f32_e32 v30, v30, v210
	v_sub_f32_e32 v31, v31, v210
	v_sub_f32_e32 v64, v64, v210
	v_sub_f32_e32 v65, v65, v210
	v_sub_f32_e32 v66, v66, v210
	v_sub_f32_e32 v67, v67, v210
	v_sub_f32_e32 v68, v68, v210
	v_sub_f32_e32 v69, v69, v210
	v_sub_f32_e32 v70, v70, v210
	v_sub_f32_e32 v71, v71, v210
	v_sub_f32_e32 v72, v72, v210
	v_sub_f32_e32 v73, v73, v210
	v_sub_f32_e32 v74, v74, v210
	v_sub_f32_e32 v75, v75, v210
	v_sub_f32_e32 v76, v76, v210
	v_sub_f32_e32 v77, v77, v210
	v_sub_f32_e32 v78, v78, v210
	v_sub_f32_e32 v79, v79, v210
	v_add_f32_e32 v162, v162, v210
	s_branch .LBB0_597

; template <bool MLA, int DK, int DV>
; __device__ __forceinline__ void attn_core(const Params& p, int b, int h, int map, int q0, int nt, char* smem,
;                                           f32x16 (&o)[DV / 32], float& lout) {
;     ...
;     if (has2) ATTN_STOREK(kt & 1);
;     if (has1) ATTN_STOREV((kt + 1) & 1);
.LBB0_597:
	s_add_i32 s60, s68, 1
	s_cmp_lt_u32 s60, s34
	s_cbranch_scc0 .Lm2w_ns
	s_and_b64 vcc, exec, s[8:9]
	s_cbranch_vccnz .Lm2w_w3
	s_waitcnt vmcnt(2)
	s_branch .Lm2w_wd

; template <bool MLA, int DK, int DV>
; __device__ __forceinline__ void attn_core(const Params& p, int b, int h, int map, int q0, int nt, char* smem,
;                                           f32x16 (&o)[DV / 32], float& lout) {
;     ...
;     if (has2) ATTN_STOREK(kt & 1);
;     if (has1) ATTN_STOREV((kt + 1) & 1);
.Lm2w_ns:
	s_cmp_lt_u32 s68, s34
	s_cbranch_scc0 .Lm2w_w0
	s_waitcnt vmcnt(1)
	s_branch .Lm2w_wd

.Lm2w_wd:
	s_andn2_b64 vcc, exec, s[72:73]
	s_cbranch_vccnz .LBB0_603
	s_and_saveexec_b64 s[16:17], s[6:7]
	s_cbranch_execz .LBB0_600
	ds_write_b128 v159, v[220:223] offset:13312
.LBB0_600:
	s_or_b64 exec, exec, s[16:17]
	s_and_saveexec_b64 s[16:17], s[8:9]
	s_cbranch_execz .LBB0_602
	ds_write_b128 v160, v[224:227] offset:13312

.LBB0_603:
	s_and_saveexec_b64 s[16:17], s[70:71]
	s_cbranch_execz .LBB0_542
	v_add_u32_e32 v132, 0x6800, v148
	ds_write2_b64 v132, v[228:229], v[230:231] offset1:1
	s_branch .LBB0_542
